# P6L: P6 epilogue issues all 16 residual loads up front (counted waits) instead of load->vmcnt(0) x16
# speedup vs baseline: 1.0123x; 1.0008x over previous
; __device__ __forceinline__ u32x4 pack8(f32x4 a, f32x4 b) { u32x4 w; w.x = cvt_pk_bf16(a[0], a[1]); w.y = cvt_pk_bf16(a[2], a[3]); w.z = cvt_pk_bf16(b[0], b[1]); w.w = cvt_pk_bf16(b[2], b[3]); return w; }
;     __device__ __forceinline__ void operator()(const f32x4 (&acc)[2][2][4][2], const pg8::Unit& u, int wr, int wc, int fr, int fq) const {
; #pragma unroll
;         for (int ai = 0; ai < 2; ++ai)
; #pragma unroll
;             for (int m = 0; m < 4; ++m) { const int row = u.pm * 256 + ai * 128 + wr * 64 + m * 16 + fr; float ss = 0.f;
; #pragma unroll
;                 for (int bj = 0; bj < 2; ++bj) { const int col = u.pn * 256 + bj * 128 + wc * 32 + 8 * fq;
;                     f32x4 x0, x1; unpack_bf16x8(*(const u32x4*)(X2B + (size_t)row * D + col), x0, x1);
;                     const f32x4 v0 = acc[ai][bj][m][0] + x0, v1 = acc[ai][bj][m][1] + x1;
;                     ss += (v0[0] * v0[0] + v0[1] * v0[1]) + (v0[2] * v0[2] + v0[3] * v0[3]) + (v1[0] * v1[0] + v1[1] * v1[1]) + (v1[2] * v1[2] + v1[3] * v1[3]);
;                     *(u32x4*)(X3B + (size_t)row * D + col) = pack8(v0, v1); }
;                 ss += __shfl_xor(ss, 16); ss += __shfl_xor(ss, 32);
;                 if (fq == 0) atomicAdd(rss + row, ss); }
.LBB0_934:
	v_lshl_add_u32 v148, s48, 4, v133
	v_lshl_or_b32 v146, s47, 8, v151
	v_ashrrev_i32_e32 v149, 31, v148
	v_lshlrev_b64 v[160:161], 11, v[148:149]
	v_ashrrev_i32_e32 v147, 31, v146
	v_lshl_add_u64 v[156:157], s[8:9], 0, v[160:161]
	v_lshlrev_b64 v[146:147], 1, v[146:147]
	v_lshl_add_u64 v[162:163], v[156:157], 0, v[146:147]
	v_mov_b64_e32 v[242:243], v[162:163]
	s_mov_b64 s[96:97], 0x8000
	s_mov_b64 s[98:99], 0x28000
	global_load_dwordx4 v[170:173], v[242:243], off
	global_load_dwordx4 v[174:177], v[242:243], off offset:256
	v_lshl_add_u64 v[242:243], v[242:243], 0, s[96:97]
	global_load_dwordx4 v[178:181], v[242:243], off
	global_load_dwordx4 v[182:185], v[242:243], off offset:256
	v_lshl_add_u64 v[242:243], v[242:243], 0, s[96:97]
	global_load_dwordx4 v[186:189], v[242:243], off
	global_load_dwordx4 v[190:193], v[242:243], off offset:256
	v_lshl_add_u64 v[242:243], v[242:243], 0, s[96:97]
	global_load_dwordx4 v[194:197], v[242:243], off
	global_load_dwordx4 v[198:201], v[242:243], off offset:256
	v_lshl_add_u64 v[242:243], v[242:243], 0, s[98:99]
	global_load_dwordx4 v[202:205], v[242:243], off
	global_load_dwordx4 v[206:209], v[242:243], off offset:256
	v_lshl_add_u64 v[242:243], v[242:243], 0, s[96:97]
	global_load_dwordx4 v[210:213], v[242:243], off
	global_load_dwordx4 v[214:217], v[242:243], off offset:256
	v_lshl_add_u64 v[242:243], v[242:243], 0, s[96:97]
	global_load_dwordx4 v[218:221], v[242:243], off
	global_load_dwordx4 v[222:225], v[242:243], off offset:256
	v_lshl_add_u64 v[242:243], v[242:243], 0, s[96:97]
	global_load_dwordx4 v[234:237], v[242:243], off
	global_load_dwordx4 v[238:241], v[242:243], off offset:256
	s_waitcnt vmcnt(15)
	v_lshlrev_b32_e32 v164, 16, v170
	v_and_b32_e32 v165, 0xffff0000, v170
	v_lshlrev_b32_e32 v156, 16, v171
	v_and_b32_e32 v157, 0xffff0000, v171
	v_lshlrev_b32_e32 v166, 16, v172
	v_and_b32_e32 v167, 0xffff0000, v172
	v_lshlrev_b32_e32 v158, 16, v173
	v_and_b32_e32 v159, 0xffff0000, v173
	v_pk_add_f32 v[126:127], v[126:127], v[156:157]
	v_pk_add_f32 v[164:165], v[124:125], v[164:165]
	v_pk_add_f32 v[168:169], v[122:123], v[158:159]
	v_pk_add_f32 v[166:167], v[120:121], v[166:167]
	v_cvt_pk_bf16_f32 v122, v164, v165
	v_cvt_pk_bf16_f32 v123, v126, v127
	v_and_b32_e32 v121, 64, v155
	v_cvt_pk_bf16_f32 v124, v166, v167
	v_cvt_pk_bf16_f32 v125, v168, v169
	v_xor_b32_e32 v120, 16, v155
	v_add_u32_e32 v121, 64, v121
	v_xor_b32_e32 v162, 32, v155
	v_cmp_lt_i32_e32 vcc, v120, v121
	v_mul_f32_e32 v127, v127, v127
	v_mul_f32_e32 v163, v167, v167
	v_cndmask_b32_e32 v120, v155, v120, vcc
	v_cmp_lt_i32_e32 vcc, v162, v121
	v_fmac_f32_e32 v127, v126, v126
	v_fmac_f32_e32 v163, v166, v166
	v_cndmask_b32_e32 v121, v155, v162, vcc
	v_mul_f32_e32 v162, v165, v165
	v_fmac_f32_e32 v162, v164, v164
	v_mul_f32_e32 v165, v169, v169
	v_add_f32_e32 v126, v162, v127
	v_fmac_f32_e32 v165, v168, v168
	v_add_f32_e32 v126, v163, v126
	v_add_f32_e32 v164, v165, v126
	v_lshlrev_b32_e32 v120, 2, v120
	s_waitcnt vmcnt(14)
	v_lshlrev_b32_e32 v126, 16, v174
	v_and_b32_e32 v127, 0xffff0000, v174
	v_lshlrev_b32_e32 v156, 16, v175
	v_and_b32_e32 v157, 0xffff0000, v175
	v_lshlrev_b32_e32 v162, 16, v176
	v_and_b32_e32 v163, 0xffff0000, v176
	v_pk_add_f32 v[118:119], v[118:119], v[156:157]
	v_pk_add_f32 v[116:117], v[116:117], v[126:127]
	v_lshlrev_b32_e32 v158, 16, v177
	v_and_b32_e32 v159, 0xffff0000, v177
	v_pk_add_f32 v[156:157], v[112:113], v[162:163]
	v_mul_f32_e32 v112, v117, v117
	v_mul_f32_e32 v113, v119, v119
	v_pk_add_f32 v[126:127], v[114:115], v[158:159]
	v_mul_f32_e32 v114, v157, v157
	v_fmac_f32_e32 v112, v116, v116
	v_fmac_f32_e32 v113, v118, v118
	v_mul_f32_e32 v115, v127, v127
	v_fmac_f32_e32 v114, v156, v156
	v_add_f32_e32 v112, v112, v113
	v_fmac_f32_e32 v115, v126, v126
	v_add_f32_e32 v112, v114, v112
	v_add_f32_e32 v112, v115, v112
	v_add_f32_e32 v114, v164, v112
	ds_bpermute_b32 v115, v120, v114
	v_lshl_add_u64 v[112:113], s[10:11], 0, v[160:161]
	v_lshl_add_u64 v[158:159], v[112:113], 0, v[146:147]
	global_store_dwordx4 v[158:159], v[122:125], off
	v_cvt_pk_bf16_f32 v116, v116, v117
	s_waitcnt lgkmcnt(0)
	v_add_f32_e32 v112, v114, v115
	v_lshlrev_b32_e32 v114, 2, v121
	ds_bpermute_b32 v113, v114, v112
	v_cvt_pk_bf16_f32 v117, v118, v119
	v_cvt_pk_bf16_f32 v118, v156, v157
	v_cvt_pk_bf16_f32 v119, v126, v127
	global_store_dwordx4 v[158:159], v[116:119], off offset:256
	s_and_saveexec_b64 s[20:21], s[2:3]
	s_cbranch_execz .LBB0_936
	v_lshl_add_u64 v[116:117], v[148:149], 2, s[12:13]
	s_waitcnt lgkmcnt(0)
	v_add_f32_e32 v112, v112, v113
	global_atomic_add_f32 v[116:117], v112, off
; __device__ __forceinline__ u32x4 pack8(f32x4 a, f32x4 b) { u32x4 w; w.x = cvt_pk_bf16(a[0], a[1]); w.y = cvt_pk_bf16(a[2], a[3]); w.z = cvt_pk_bf16(b[0], b[1]); w.w = cvt_pk_bf16(b[2], b[3]); return w; }
;     __device__ __forceinline__ void operator()(const f32x4 (&acc)[2][2][4][2], const pg8::Unit& u, int wr, int wc, int fr, int fq) const {
; #pragma unroll
;         for (int ai = 0; ai < 2; ++ai)
; #pragma unroll
;             for (int m = 0; m < 4; ++m) { const int row = u.pm * 256 + ai * 128 + wr * 64 + m * 16 + fr; float ss = 0.f;
; #pragma unroll
;                 for (int bj = 0; bj < 2; ++bj) { const int col = u.pn * 256 + bj * 128 + wc * 32 + 8 * fq;
;                     f32x4 x0, x1; unpack_bf16x8(*(const u32x4*)(X2B + (size_t)row * D + col), x0, x1);
;                     const f32x4 v0 = acc[ai][bj][m][0] + x0, v1 = acc[ai][bj][m][1] + x1;
;                     ss += (v0[0] * v0[0] + v0[1] * v0[1]) + (v0[2] * v0[2] + v0[3] * v0[3]) + (v1[0] * v1[0] + v1[1] * v1[1]) + (v1[2] * v1[2] + v1[3] * v1[3]);
;                     *(u32x4*)(X3B + (size_t)row * D + col) = pack8(v0, v1); }
;                 ss += __shfl_xor(ss, 16); ss += __shfl_xor(ss, 32);
;                 if (fq == 0) atomicAdd(rss + row, ss); }
.LBB0_936:
	s_or_b64 exec, exec, s[20:21]
	v_add_u32_e32 v112, 16, v148
	s_waitcnt lgkmcnt(0)
	v_ashrrev_i32_e32 v113, 31, v112
	v_lshlrev_b64 v[122:123], 11, v[112:113]
	v_lshl_add_u64 v[116:117], s[8:9], 0, v[122:123]
	v_lshl_add_u64 v[124:125], v[116:117], 0, v[146:147]
	s_waitcnt vmcnt(15)
	v_lshlrev_b32_e32 v126, 16, v178
	v_and_b32_e32 v127, 0xffff0000, v178
	v_lshlrev_b32_e32 v116, 16, v179
	v_and_b32_e32 v117, 0xffff0000, v179
	v_lshlrev_b32_e32 v156, 16, v180
	v_and_b32_e32 v157, 0xffff0000, v180
	v_lshlrev_b32_e32 v118, 16, v181
	v_and_b32_e32 v119, 0xffff0000, v181
	v_pk_add_f32 v[116:117], v[110:111], v[116:117]
	v_pk_add_f32 v[126:127], v[108:109], v[126:127]
	v_pk_add_f32 v[118:119], v[106:107], v[118:119]
	v_pk_add_f32 v[156:157], v[104:105], v[156:157]
	v_cvt_pk_bf16_f32 v104, v126, v127
	v_cvt_pk_bf16_f32 v105, v116, v117
	v_mul_f32_e32 v115, v127, v127
	v_cvt_pk_bf16_f32 v106, v156, v157
	v_cvt_pk_bf16_f32 v107, v118, v119
	v_mul_f32_e32 v117, v117, v117
	v_mul_f32_e32 v121, v157, v157
	v_fmac_f32_e32 v115, v126, v126
	v_fmac_f32_e32 v117, v116, v116
	v_mul_f32_e32 v119, v119, v119
	v_fmac_f32_e32 v121, v156, v156
	v_add_f32_e32 v115, v115, v117
	v_fmac_f32_e32 v119, v118, v118
	v_add_f32_e32 v115, v121, v115
	v_add_f32_e32 v115, v119, v115
	s_waitcnt vmcnt(14)
	v_lshlrev_b32_e32 v116, 16, v182
	v_and_b32_e32 v117, 0xffff0000, v182
	v_lshlrev_b32_e32 v108, 16, v183
	v_and_b32_e32 v109, 0xffff0000, v183
	v_lshlrev_b32_e32 v118, 16, v184
	v_and_b32_e32 v119, 0xffff0000, v184
	v_lshlrev_b32_e32 v110, 16, v185
	v_and_b32_e32 v111, 0xffff0000, v185
	v_pk_add_f32 v[102:103], v[102:103], v[108:109]
	v_pk_add_f32 v[100:101], v[100:101], v[116:117]
	v_pk_add_f32 v[108:109], v[98:99], v[110:111]
	v_pk_add_f32 v[110:111], v[96:97], v[118:119]
	v_mul_f32_e32 v96, v101, v101
	v_mul_f32_e32 v97, v103, v103
	v_mul_f32_e32 v98, v111, v111
	v_fmac_f32_e32 v96, v100, v100
	v_fmac_f32_e32 v97, v102, v102
	v_mul_f32_e32 v99, v109, v109
	v_fmac_f32_e32 v98, v110, v110
	v_add_f32_e32 v96, v96, v97
	v_add_f32_e32 v96, v98, v96
	v_fmac_f32_e32 v99, v108, v108
	v_add_f32_e32 v96, v99, v96
	v_add_f32_e32 v99, v115, v96
	ds_bpermute_b32 v115, v120, v99
	v_lshl_add_u64 v[96:97], s[10:11], 0, v[122:123]
	v_lshl_add_u64 v[116:117], v[96:97], 0, v[146:147]
	global_store_dwordx4 v[116:117], v[104:107], off
	v_cvt_pk_bf16_f32 v98, v100, v101
	s_waitcnt lgkmcnt(0)
	v_add_f32_e32 v96, v99, v115
	ds_bpermute_b32 v97, v114, v96
	v_cvt_pk_bf16_f32 v99, v102, v103
	v_cvt_pk_bf16_f32 v100, v110, v111
	v_cvt_pk_bf16_f32 v101, v108, v109
	global_store_dwordx4 v[116:117], v[98:101], off offset:256
	s_and_saveexec_b64 s[20:21], s[2:3]
	s_cbranch_execz .LBB0_938
	v_lshl_add_u64 v[98:99], v[112:113], 2, s[12:13]
	s_waitcnt lgkmcnt(0)
	v_add_f32_e32 v96, v96, v97
	global_atomic_add_f32 v[98:99], v96, off
.LBB0_938:
	s_or_b64 exec, exec, s[20:21]
	v_add_u32_e32 v96, 32, v148
	s_waitcnt lgkmcnt(0)
	v_ashrrev_i32_e32 v97, 31, v96
	v_lshlrev_b64 v[102:103], 11, v[96:97]
	v_lshl_add_u64 v[98:99], s[8:9], 0, v[102:103]
	v_lshl_add_u64 v[104:105], v[98:99], 0, v[146:147]
	s_waitcnt vmcnt(15)
	v_lshlrev_b32_e32 v106, 16, v186
	v_and_b32_e32 v107, 0xffff0000, v186
	v_lshlrev_b32_e32 v98, 16, v187
	v_and_b32_e32 v99, 0xffff0000, v187
	v_lshlrev_b32_e32 v108, 16, v188
	v_and_b32_e32 v109, 0xffff0000, v188
	v_lshlrev_b32_e32 v100, 16, v189
	v_and_b32_e32 v101, 0xffff0000, v189
	v_pk_add_f32 v[98:99], v[94:95], v[98:99]
	v_pk_add_f32 v[106:107], v[92:93], v[106:107]
	v_pk_add_f32 v[100:101], v[90:91], v[100:101]
	v_pk_add_f32 v[108:109], v[88:89], v[108:109]
	v_cvt_pk_bf16_f32 v88, v106, v107
	v_cvt_pk_bf16_f32 v89, v98, v99
	v_mul_f32_e32 v99, v99, v99
	v_cvt_pk_bf16_f32 v90, v108, v109
	v_cvt_pk_bf16_f32 v91, v100, v101
	v_mul_f32_e32 v104, v107, v107
	v_mul_f32_e32 v105, v109, v109
	v_fmac_f32_e32 v104, v106, v106
	v_fmac_f32_e32 v99, v98, v98
	v_mul_f32_e32 v101, v101, v101
	v_fmac_f32_e32 v105, v108, v108
	v_add_f32_e32 v98, v104, v99
	v_fmac_f32_e32 v101, v100, v100
	v_add_f32_e32 v98, v105, v98
	v_add_f32_e32 v104, v101, v98
	s_waitcnt vmcnt(14)
	v_lshlrev_b32_e32 v98, 16, v190
	v_and_b32_e32 v99, 0xffff0000, v190
	v_lshlrev_b32_e32 v92, 16, v191
	v_and_b32_e32 v93, 0xffff0000, v191
	v_lshlrev_b32_e32 v100, 16, v192
	v_and_b32_e32 v101, 0xffff0000, v192
	v_lshlrev_b32_e32 v94, 16, v193
	v_and_b32_e32 v95, 0xffff0000, v193
	v_pk_add_f32 v[86:87], v[86:87], v[92:93]
	v_pk_add_f32 v[84:85], v[84:85], v[98:99]
	v_pk_add_f32 v[92:93], v[82:83], v[94:95]
	v_pk_add_f32 v[94:95], v[80:81], v[100:101]
	v_mul_f32_e32 v80, v85, v85
	v_mul_f32_e32 v81, v87, v87
	v_mul_f32_e32 v82, v95, v95
	v_fmac_f32_e32 v80, v84, v84
	v_fmac_f32_e32 v81, v86, v86
	v_mul_f32_e32 v83, v93, v93
	v_fmac_f32_e32 v82, v94, v94
	v_add_f32_e32 v80, v80, v81
	v_add_f32_e32 v80, v82, v80
	v_fmac_f32_e32 v83, v92, v92
	v_add_f32_e32 v80, v83, v80
	v_add_f32_e32 v83, v104, v80
	ds_bpermute_b32 v100, v120, v83
	v_lshl_add_u64 v[80:81], s[10:11], 0, v[102:103]
	v_lshl_add_u64 v[98:99], v[80:81], 0, v[146:147]
	global_store_dwordx4 v[98:99], v[88:91], off
	v_cvt_pk_bf16_f32 v82, v84, v85
	s_waitcnt lgkmcnt(0)
	v_add_f32_e32 v80, v83, v100
	ds_bpermute_b32 v81, v114, v80
	v_cvt_pk_bf16_f32 v83, v86, v87
	v_cvt_pk_bf16_f32 v84, v94, v95
	v_cvt_pk_bf16_f32 v85, v92, v93
	global_store_dwordx4 v[98:99], v[82:85], off offset:256
	s_and_saveexec_b64 s[20:21], s[2:3]
	s_cbranch_execz .LBB0_940
	v_lshl_add_u64 v[82:83], v[96:97], 2, s[12:13]
	s_waitcnt lgkmcnt(0)
	v_add_f32_e32 v80, v80, v81
	global_atomic_add_f32 v[82:83], v80, off
; __device__ __forceinline__ u32x4 pack8(f32x4 a, f32x4 b) { u32x4 w; w.x = cvt_pk_bf16(a[0], a[1]); w.y = cvt_pk_bf16(a[2], a[3]); w.z = cvt_pk_bf16(b[0], b[1]); w.w = cvt_pk_bf16(b[2], b[3]); return w; }
;     __device__ __forceinline__ void operator()(const f32x4 (&acc)[2][2][4][2], const pg8::Unit& u, int wr, int wc, int fr, int fq) const {
; #pragma unroll
;         for (int ai = 0; ai < 2; ++ai)
; #pragma unroll
;             for (int m = 0; m < 4; ++m) { const int row = u.pm * 256 + ai * 128 + wr * 64 + m * 16 + fr; float ss = 0.f;
; #pragma unroll
;                 for (int bj = 0; bj < 2; ++bj) { const int col = u.pn * 256 + bj * 128 + wc * 32 + 8 * fq;
;                     f32x4 x0, x1; unpack_bf16x8(*(const u32x4*)(X2B + (size_t)row * D + col), x0, x1);
;                     const f32x4 v0 = acc[ai][bj][m][0] + x0, v1 = acc[ai][bj][m][1] + x1;
;                     ss += (v0[0] * v0[0] + v0[1] * v0[1]) + (v0[2] * v0[2] + v0[3] * v0[3]) + (v1[0] * v1[0] + v1[1] * v1[1]) + (v1[2] * v1[2] + v1[3] * v1[3]);
;                     *(u32x4*)(X3B + (size_t)row * D + col) = pack8(v0, v1); }
;                 ss += __shfl_xor(ss, 16); ss += __shfl_xor(ss, 32);
;                 if (fq == 0) atomicAdd(rss + row, ss); }
.LBB0_940:
	s_or_b64 exec, exec, s[20:21]
	v_add_u32_e32 v80, 48, v148
	s_waitcnt lgkmcnt(0)
	v_ashrrev_i32_e32 v81, 31, v80
	v_lshlrev_b64 v[86:87], 11, v[80:81]
	v_lshl_add_u64 v[82:83], s[8:9], 0, v[86:87]
	v_lshl_add_u64 v[88:89], v[82:83], 0, v[146:147]
	s_waitcnt vmcnt(15)
	v_lshlrev_b32_e32 v90, 16, v194
	v_and_b32_e32 v91, 0xffff0000, v194
	v_lshlrev_b32_e32 v82, 16, v195
	v_and_b32_e32 v83, 0xffff0000, v195
	v_lshlrev_b32_e32 v92, 16, v196
	v_and_b32_e32 v93, 0xffff0000, v196
	v_lshlrev_b32_e32 v84, 16, v197
	v_and_b32_e32 v85, 0xffff0000, v197
	v_pk_add_f32 v[82:83], v[78:79], v[82:83]
	v_pk_add_f32 v[90:91], v[76:77], v[90:91]
	v_pk_add_f32 v[84:85], v[74:75], v[84:85]
	v_pk_add_f32 v[92:93], v[72:73], v[92:93]
	v_cvt_pk_bf16_f32 v72, v90, v91
	v_cvt_pk_bf16_f32 v73, v82, v83
	v_mul_f32_e32 v83, v83, v83
	v_cvt_pk_bf16_f32 v74, v92, v93
	v_cvt_pk_bf16_f32 v75, v84, v85
	v_mul_f32_e32 v88, v91, v91
	v_mul_f32_e32 v89, v93, v93
	v_fmac_f32_e32 v88, v90, v90
	v_fmac_f32_e32 v83, v82, v82
	v_mul_f32_e32 v85, v85, v85
	v_fmac_f32_e32 v89, v92, v92
	v_add_f32_e32 v82, v88, v83
	v_fmac_f32_e32 v85, v84, v84
	v_add_f32_e32 v82, v89, v82
	v_add_f32_e32 v88, v85, v82
	s_waitcnt vmcnt(14)
	v_lshlrev_b32_e32 v82, 16, v198
	v_and_b32_e32 v83, 0xffff0000, v198
	v_lshlrev_b32_e32 v76, 16, v199
	v_and_b32_e32 v77, 0xffff0000, v199
	v_lshlrev_b32_e32 v84, 16, v200
	v_and_b32_e32 v85, 0xffff0000, v200
	v_lshlrev_b32_e32 v78, 16, v201
	v_and_b32_e32 v79, 0xffff0000, v201
	v_pk_add_f32 v[70:71], v[70:71], v[76:77]
	v_pk_add_f32 v[68:69], v[68:69], v[82:83]
	v_pk_add_f32 v[76:77], v[66:67], v[78:79]
	v_pk_add_f32 v[78:79], v[64:65], v[84:85]
	v_mul_f32_e32 v64, v69, v69
	v_mul_f32_e32 v65, v71, v71
	v_mul_f32_e32 v66, v79, v79
	v_fmac_f32_e32 v64, v68, v68
	v_fmac_f32_e32 v65, v70, v70
	v_mul_f32_e32 v67, v77, v77
	v_fmac_f32_e32 v66, v78, v78
	v_add_f32_e32 v64, v64, v65
	v_add_f32_e32 v64, v66, v64
	v_fmac_f32_e32 v67, v76, v76
	v_add_f32_e32 v64, v67, v64
	v_add_f32_e32 v67, v88, v64
	ds_bpermute_b32 v84, v120, v67
	v_lshl_add_u64 v[64:65], s[10:11], 0, v[86:87]
	v_lshl_add_u64 v[82:83], v[64:65], 0, v[146:147]
	global_store_dwordx4 v[82:83], v[72:75], off
	v_cvt_pk_bf16_f32 v66, v68, v69
	s_waitcnt lgkmcnt(0)
	v_add_f32_e32 v64, v67, v84
	ds_bpermute_b32 v65, v114, v64
	v_cvt_pk_bf16_f32 v67, v70, v71
	v_cvt_pk_bf16_f32 v68, v78, v79
	v_cvt_pk_bf16_f32 v69, v76, v77
	global_store_dwordx4 v[82:83], v[66:69], off offset:256
	s_and_saveexec_b64 s[20:21], s[2:3]
	s_cbranch_execz .LBB0_942
	v_lshl_add_u64 v[66:67], v[80:81], 2, s[12:13]
	s_waitcnt lgkmcnt(0)
	v_add_f32_e32 v64, v64, v65
	global_atomic_add_f32 v[66:67], v64, off
.LBB0_942:
	s_or_b64 exec, exec, s[20:21]
	v_add_u32_e32 v64, 0x80, v148
	s_waitcnt lgkmcnt(0)
	v_ashrrev_i32_e32 v65, 31, v64
	v_lshlrev_b64 v[70:71], 11, v[64:65]
	v_lshl_add_u64 v[66:67], s[8:9], 0, v[70:71]
	v_lshl_add_u64 v[72:73], v[66:67], 0, v[146:147]
	s_waitcnt vmcnt(15)
	v_lshlrev_b32_e32 v74, 16, v202
	v_and_b32_e32 v75, 0xffff0000, v202
	v_lshlrev_b32_e32 v66, 16, v203
	v_and_b32_e32 v67, 0xffff0000, v203
	v_lshlrev_b32_e32 v76, 16, v204
	v_and_b32_e32 v77, 0xffff0000, v204
	v_lshlrev_b32_e32 v68, 16, v205
	v_and_b32_e32 v69, 0xffff0000, v205
	v_pk_add_f32 v[66:67], v[62:63], v[66:67]
	v_pk_add_f32 v[74:75], v[60:61], v[74:75]
	v_pk_add_f32 v[68:69], v[58:59], v[68:69]
	v_pk_add_f32 v[76:77], v[56:57], v[76:77]
	v_cvt_pk_bf16_f32 v56, v74, v75
	v_cvt_pk_bf16_f32 v57, v66, v67
	v_mul_f32_e32 v67, v67, v67
	v_cvt_pk_bf16_f32 v58, v76, v77
	v_cvt_pk_bf16_f32 v59, v68, v69
	v_mul_f32_e32 v72, v75, v75
	v_mul_f32_e32 v73, v77, v77
	v_fmac_f32_e32 v72, v74, v74
	v_fmac_f32_e32 v67, v66, v66
	v_mul_f32_e32 v69, v69, v69
	v_fmac_f32_e32 v73, v76, v76
	v_add_f32_e32 v66, v72, v67
	v_fmac_f32_e32 v69, v68, v68
	v_add_f32_e32 v66, v73, v66
	v_add_f32_e32 v72, v69, v66
	s_waitcnt vmcnt(14)
	v_lshlrev_b32_e32 v66, 16, v206
	v_and_b32_e32 v67, 0xffff0000, v206
	v_lshlrev_b32_e32 v60, 16, v207
	v_and_b32_e32 v61, 0xffff0000, v207
	v_lshlrev_b32_e32 v68, 16, v208
	v_and_b32_e32 v69, 0xffff0000, v208
	v_lshlrev_b32_e32 v62, 16, v209
	v_and_b32_e32 v63, 0xffff0000, v209
	v_pk_add_f32 v[54:55], v[54:55], v[60:61]
	v_pk_add_f32 v[52:53], v[52:53], v[66:67]
	v_pk_add_f32 v[60:61], v[50:51], v[62:63]
	v_pk_add_f32 v[62:63], v[48:49], v[68:69]
	v_mul_f32_e32 v48, v53, v53
	v_mul_f32_e32 v49, v55, v55
	v_mul_f32_e32 v50, v63, v63
	v_fmac_f32_e32 v48, v52, v52
	v_fmac_f32_e32 v49, v54, v54
	v_mul_f32_e32 v51, v61, v61
	v_fmac_f32_e32 v50, v62, v62
	v_add_f32_e32 v48, v48, v49
	v_add_f32_e32 v48, v50, v48
	v_fmac_f32_e32 v51, v60, v60
	v_add_f32_e32 v48, v51, v48
	v_add_f32_e32 v51, v72, v48
	ds_bpermute_b32 v68, v120, v51
	v_lshl_add_u64 v[48:49], s[10:11], 0, v[70:71]
	v_lshl_add_u64 v[66:67], v[48:49], 0, v[146:147]
	global_store_dwordx4 v[66:67], v[56:59], off
	v_cvt_pk_bf16_f32 v50, v52, v53
	s_waitcnt lgkmcnt(0)
	v_add_f32_e32 v48, v51, v68
	ds_bpermute_b32 v49, v114, v48
	v_cvt_pk_bf16_f32 v51, v54, v55
	v_cvt_pk_bf16_f32 v52, v62, v63
	v_cvt_pk_bf16_f32 v53, v60, v61
	global_store_dwordx4 v[66:67], v[50:53], off offset:256
	s_and_saveexec_b64 s[20:21], s[2:3]
	s_cbranch_execz .LBB0_944
	v_lshl_add_u64 v[50:51], v[64:65], 2, s[12:13]
	s_waitcnt lgkmcnt(0)
	v_add_f32_e32 v48, v48, v49
	global_atomic_add_f32 v[50:51], v48, off
; __device__ __forceinline__ u32x4 pack8(f32x4 a, f32x4 b) { u32x4 w; w.x = cvt_pk_bf16(a[0], a[1]); w.y = cvt_pk_bf16(a[2], a[3]); w.z = cvt_pk_bf16(b[0], b[1]); w.w = cvt_pk_bf16(b[2], b[3]); return w; }
;     __device__ __forceinline__ void operator()(const f32x4 (&acc)[2][2][4][2], const pg8::Unit& u, int wr, int wc, int fr, int fq) const {
; #pragma unroll
;         for (int ai = 0; ai < 2; ++ai)
; #pragma unroll
;             for (int m = 0; m < 4; ++m) { const int row = u.pm * 256 + ai * 128 + wr * 64 + m * 16 + fr; float ss = 0.f;
; #pragma unroll
;                 for (int bj = 0; bj < 2; ++bj) { const int col = u.pn * 256 + bj * 128 + wc * 32 + 8 * fq;
;                     f32x4 x0, x1; unpack_bf16x8(*(const u32x4*)(X2B + (size_t)row * D + col), x0, x1);
;                     const f32x4 v0 = acc[ai][bj][m][0] + x0, v1 = acc[ai][bj][m][1] + x1;
;                     ss += (v0[0] * v0[0] + v0[1] * v0[1]) + (v0[2] * v0[2] + v0[3] * v0[3]) + (v1[0] * v1[0] + v1[1] * v1[1]) + (v1[2] * v1[2] + v1[3] * v1[3]);
;                     *(u32x4*)(X3B + (size_t)row * D + col) = pack8(v0, v1); }
;                 ss += __shfl_xor(ss, 16); ss += __shfl_xor(ss, 32);
;                 if (fq == 0) atomicAdd(rss + row, ss); }
.LBB0_944:
	s_or_b64 exec, exec, s[20:21]
	v_add_u32_e32 v48, 0x90, v148
	s_waitcnt lgkmcnt(0)
	v_ashrrev_i32_e32 v49, 31, v48
	v_lshlrev_b64 v[54:55], 11, v[48:49]
	v_lshl_add_u64 v[50:51], s[8:9], 0, v[54:55]
	v_lshl_add_u64 v[56:57], v[50:51], 0, v[146:147]
	s_waitcnt vmcnt(15)
	v_lshlrev_b32_e32 v58, 16, v210
	v_and_b32_e32 v59, 0xffff0000, v210
	v_lshlrev_b32_e32 v50, 16, v211
	v_and_b32_e32 v51, 0xffff0000, v211
	v_lshlrev_b32_e32 v60, 16, v212
	v_and_b32_e32 v61, 0xffff0000, v212
	v_lshlrev_b32_e32 v52, 16, v213
	v_and_b32_e32 v53, 0xffff0000, v213
	v_pk_add_f32 v[50:51], v[46:47], v[50:51]
	v_pk_add_f32 v[58:59], v[44:45], v[58:59]
	v_pk_add_f32 v[52:53], v[42:43], v[52:53]
	v_pk_add_f32 v[60:61], v[40:41], v[60:61]
	v_cvt_pk_bf16_f32 v40, v58, v59
	v_cvt_pk_bf16_f32 v41, v50, v51
	v_mul_f32_e32 v51, v51, v51
	v_cvt_pk_bf16_f32 v42, v60, v61
	v_cvt_pk_bf16_f32 v43, v52, v53
	v_mul_f32_e32 v56, v59, v59
	v_mul_f32_e32 v57, v61, v61
	v_fmac_f32_e32 v56, v58, v58
	v_fmac_f32_e32 v51, v50, v50
	v_mul_f32_e32 v53, v53, v53
	v_fmac_f32_e32 v57, v60, v60
	v_add_f32_e32 v50, v56, v51
	v_fmac_f32_e32 v53, v52, v52
	v_add_f32_e32 v50, v57, v50
	v_add_f32_e32 v56, v53, v50
	s_waitcnt vmcnt(14)
	v_lshlrev_b32_e32 v50, 16, v214
	v_and_b32_e32 v51, 0xffff0000, v214
	v_lshlrev_b32_e32 v44, 16, v215
	v_and_b32_e32 v45, 0xffff0000, v215
	v_lshlrev_b32_e32 v52, 16, v216
	v_and_b32_e32 v53, 0xffff0000, v216
	v_lshlrev_b32_e32 v46, 16, v217
	v_and_b32_e32 v47, 0xffff0000, v217
	v_pk_add_f32 v[38:39], v[38:39], v[44:45]
	v_pk_add_f32 v[36:37], v[36:37], v[50:51]
	v_pk_add_f32 v[44:45], v[34:35], v[46:47]
	v_pk_add_f32 v[46:47], v[32:33], v[52:53]
	v_mul_f32_e32 v32, v37, v37
	v_mul_f32_e32 v33, v39, v39
	v_mul_f32_e32 v34, v47, v47
	v_fmac_f32_e32 v32, v36, v36
	v_fmac_f32_e32 v33, v38, v38
	v_mul_f32_e32 v35, v45, v45
	v_fmac_f32_e32 v34, v46, v46
	v_add_f32_e32 v32, v32, v33
	v_add_f32_e32 v32, v34, v32
	v_fmac_f32_e32 v35, v44, v44
	v_add_f32_e32 v32, v35, v32
	v_add_f32_e32 v35, v56, v32
	ds_bpermute_b32 v52, v120, v35
	v_lshl_add_u64 v[32:33], s[10:11], 0, v[54:55]
	v_lshl_add_u64 v[50:51], v[32:33], 0, v[146:147]
	global_store_dwordx4 v[50:51], v[40:43], off
	v_cvt_pk_bf16_f32 v34, v36, v37
	s_waitcnt lgkmcnt(0)
	v_add_f32_e32 v32, v35, v52
	ds_bpermute_b32 v33, v114, v32
	v_cvt_pk_bf16_f32 v35, v38, v39
	v_cvt_pk_bf16_f32 v36, v46, v47
	v_cvt_pk_bf16_f32 v37, v44, v45
	global_store_dwordx4 v[50:51], v[34:37], off offset:256
	s_and_saveexec_b64 s[20:21], s[2:3]
	s_cbranch_execz .LBB0_946
	v_lshl_add_u64 v[34:35], v[48:49], 2, s[12:13]
	s_waitcnt lgkmcnt(0)
	v_add_f32_e32 v32, v32, v33
	global_atomic_add_f32 v[34:35], v32, off
; __device__ __forceinline__ u32x4 pack8(f32x4 a, f32x4 b) { u32x4 w; w.x = cvt_pk_bf16(a[0], a[1]); w.y = cvt_pk_bf16(a[2], a[3]); w.z = cvt_pk_bf16(b[0], b[1]); w.w = cvt_pk_bf16(b[2], b[3]); return w; }
;     __device__ __forceinline__ void operator()(const f32x4 (&acc)[2][2][4][2], const pg8::Unit& u, int wr, int wc, int fr, int fq) const {
; #pragma unroll
;         for (int ai = 0; ai < 2; ++ai)
; #pragma unroll
;             for (int m = 0; m < 4; ++m) { const int row = u.pm * 256 + ai * 128 + wr * 64 + m * 16 + fr; float ss = 0.f;
; #pragma unroll
;                 for (int bj = 0; bj < 2; ++bj) { const int col = u.pn * 256 + bj * 128 + wc * 32 + 8 * fq;
;                     f32x4 x0, x1; unpack_bf16x8(*(const u32x4*)(X2B + (size_t)row * D + col), x0, x1);
;                     const f32x4 v0 = acc[ai][bj][m][0] + x0, v1 = acc[ai][bj][m][1] + x1;
;                     ss += (v0[0] * v0[0] + v0[1] * v0[1]) + (v0[2] * v0[2] + v0[3] * v0[3]) + (v1[0] * v1[0] + v1[1] * v1[1]) + (v1[2] * v1[2] + v1[3] * v1[3]);
;                     *(u32x4*)(X3B + (size_t)row * D + col) = pack8(v0, v1); }
;                 ss += __shfl_xor(ss, 16); ss += __shfl_xor(ss, 32);
;                 if (fq == 0) atomicAdd(rss + row, ss); }
;     }
.LBB0_946:
	s_or_b64 exec, exec, s[20:21]
	v_add_u32_e32 v32, 0xa0, v148
	s_waitcnt lgkmcnt(0)
	v_ashrrev_i32_e32 v33, 31, v32
	v_lshlrev_b64 v[38:39], 11, v[32:33]
	v_lshl_add_u64 v[34:35], s[8:9], 0, v[38:39]
	v_lshl_add_u64 v[40:41], v[34:35], 0, v[146:147]
	s_waitcnt vmcnt(15)
	v_lshlrev_b32_e32 v42, 16, v218
	v_and_b32_e32 v43, 0xffff0000, v218
	v_lshlrev_b32_e32 v34, 16, v219
	v_and_b32_e32 v35, 0xffff0000, v219
	v_lshlrev_b32_e32 v44, 16, v220
	v_and_b32_e32 v45, 0xffff0000, v220
	v_lshlrev_b32_e32 v36, 16, v221
	v_and_b32_e32 v37, 0xffff0000, v221
	v_pk_add_f32 v[34:35], v[30:31], v[34:35]
	v_pk_add_f32 v[42:43], v[28:29], v[42:43]
	v_pk_add_f32 v[36:37], v[26:27], v[36:37]
	v_pk_add_f32 v[44:45], v[24:25], v[44:45]
	v_cvt_pk_bf16_f32 v24, v42, v43
	v_cvt_pk_bf16_f32 v25, v34, v35
	v_mul_f32_e32 v35, v35, v35
	v_cvt_pk_bf16_f32 v26, v44, v45
	v_cvt_pk_bf16_f32 v27, v36, v37
	v_mul_f32_e32 v40, v43, v43
	v_mul_f32_e32 v41, v45, v45
	v_fmac_f32_e32 v40, v42, v42
	v_fmac_f32_e32 v35, v34, v34
	v_mul_f32_e32 v37, v37, v37
	v_fmac_f32_e32 v41, v44, v44
	v_add_f32_e32 v34, v40, v35
	v_fmac_f32_e32 v37, v36, v36
	v_add_f32_e32 v34, v41, v34
	v_add_f32_e32 v40, v37, v34
	s_waitcnt vmcnt(14)
	v_lshlrev_b32_e32 v34, 16, v222
	v_and_b32_e32 v35, 0xffff0000, v222
	v_lshlrev_b32_e32 v28, 16, v223
	v_and_b32_e32 v29, 0xffff0000, v223
	v_lshlrev_b32_e32 v36, 16, v224
	v_and_b32_e32 v37, 0xffff0000, v224
	v_lshlrev_b32_e32 v30, 16, v225
	v_and_b32_e32 v31, 0xffff0000, v225
	v_pk_add_f32 v[22:23], v[22:23], v[28:29]
	v_pk_add_f32 v[20:21], v[20:21], v[34:35]
	v_pk_add_f32 v[28:29], v[18:19], v[30:31]
	v_pk_add_f32 v[30:31], v[16:17], v[36:37]
	v_mul_f32_e32 v16, v21, v21
	v_mul_f32_e32 v17, v23, v23
	v_mul_f32_e32 v18, v31, v31
	v_fmac_f32_e32 v16, v20, v20
	v_fmac_f32_e32 v17, v22, v22
	v_mul_f32_e32 v19, v29, v29
	v_fmac_f32_e32 v18, v30, v30
	v_add_f32_e32 v16, v16, v17
	v_add_f32_e32 v16, v18, v16
	v_fmac_f32_e32 v19, v28, v28
	v_add_f32_e32 v16, v19, v16
	v_add_f32_e32 v19, v40, v16
	ds_bpermute_b32 v36, v120, v19
	v_lshl_add_u64 v[16:17], s[10:11], 0, v[38:39]
	v_lshl_add_u64 v[34:35], v[16:17], 0, v[146:147]
	global_store_dwordx4 v[34:35], v[24:27], off
	v_cvt_pk_bf16_f32 v18, v20, v21
	s_waitcnt lgkmcnt(0)
	v_add_f32_e32 v16, v19, v36
	ds_bpermute_b32 v17, v114, v16
	v_cvt_pk_bf16_f32 v19, v22, v23
	v_cvt_pk_bf16_f32 v20, v30, v31
	v_cvt_pk_bf16_f32 v21, v28, v29
	global_store_dwordx4 v[34:35], v[18:21], off offset:256
	s_and_saveexec_b64 s[20:21], s[2:3]
	s_cbranch_execz .LBB0_948
	v_lshl_add_u64 v[18:19], v[32:33], 2, s[12:13]
	s_waitcnt lgkmcnt(0)
	v_add_f32_e32 v16, v16, v17
	global_atomic_add_f32 v[18:19], v16, off
.LBB0_948:
	s_or_b64 exec, exec, s[20:21]
	v_add_u32_e32 v16, 0xb0, v148
	s_waitcnt lgkmcnt(0)
	v_ashrrev_i32_e32 v17, 31, v16
	v_lshlrev_b64 v[22:23], 11, v[16:17]
	v_lshl_add_u64 v[18:19], s[8:9], 0, v[22:23]
	v_lshl_add_u64 v[24:25], v[18:19], 0, v[146:147]
	s_waitcnt vmcnt(15)
	v_lshlrev_b32_e32 v26, 16, v234
	v_and_b32_e32 v27, 0xffff0000, v234
	v_lshlrev_b32_e32 v18, 16, v235
	v_and_b32_e32 v19, 0xffff0000, v235
	v_lshlrev_b32_e32 v28, 16, v236
	v_and_b32_e32 v29, 0xffff0000, v236
	v_lshlrev_b32_e32 v20, 16, v237
	v_and_b32_e32 v21, 0xffff0000, v237
	v_pk_add_f32 v[18:19], v[14:15], v[18:19]
	v_pk_add_f32 v[26:27], v[12:13], v[26:27]
	v_pk_add_f32 v[20:21], v[10:11], v[20:21]
	v_pk_add_f32 v[28:29], v[8:9], v[28:29]
	v_cvt_pk_bf16_f32 v8, v26, v27
	v_cvt_pk_bf16_f32 v9, v18, v19
	v_mul_f32_e32 v19, v19, v19
	v_cvt_pk_bf16_f32 v10, v28, v29
	v_cvt_pk_bf16_f32 v11, v20, v21
	v_mul_f32_e32 v24, v27, v27
	v_mul_f32_e32 v25, v29, v29
	v_fmac_f32_e32 v24, v26, v26
	v_fmac_f32_e32 v19, v18, v18
	v_mul_f32_e32 v21, v21, v21
	v_fmac_f32_e32 v25, v28, v28
	v_add_f32_e32 v18, v24, v19
	v_fmac_f32_e32 v21, v20, v20
	v_add_f32_e32 v18, v25, v18
	v_add_f32_e32 v24, v21, v18
	s_waitcnt vmcnt(14)
	v_lshlrev_b32_e32 v18, 16, v238
	v_and_b32_e32 v19, 0xffff0000, v238
	v_lshlrev_b32_e32 v12, 16, v239
	v_and_b32_e32 v13, 0xffff0000, v239
	v_lshlrev_b32_e32 v20, 16, v240
	v_and_b32_e32 v21, 0xffff0000, v240
	v_lshlrev_b32_e32 v14, 16, v241
	v_and_b32_e32 v15, 0xffff0000, v241
	v_pk_add_f32 v[6:7], v[6:7], v[12:13]
	v_pk_add_f32 v[4:5], v[4:5], v[18:19]
	v_pk_add_f32 v[12:13], v[2:3], v[14:15]
	v_pk_add_f32 v[14:15], v[0:1], v[20:21]
	v_mul_f32_e32 v0, v5, v5
	v_mul_f32_e32 v1, v7, v7
	v_mul_f32_e32 v2, v15, v15
	v_fmac_f32_e32 v0, v4, v4
	v_fmac_f32_e32 v1, v6, v6
	v_mul_f32_e32 v3, v13, v13
	v_fmac_f32_e32 v2, v14, v14
	v_add_f32_e32 v0, v0, v1
	v_add_f32_e32 v0, v2, v0
	v_fmac_f32_e32 v3, v12, v12
	v_add_f32_e32 v0, v3, v0
	v_add_f32_e32 v3, v24, v0
	ds_bpermute_b32 v20, v120, v3
	v_lshl_add_u64 v[0:1], s[10:11], 0, v[22:23]
	v_lshl_add_u64 v[18:19], v[0:1], 0, v[146:147]
	global_store_dwordx4 v[18:19], v[8:11], off
	v_cvt_pk_bf16_f32 v2, v4, v5
	s_waitcnt lgkmcnt(0)
	v_add_f32_e32 v0, v3, v20
	ds_bpermute_b32 v1, v114, v0
	v_cvt_pk_bf16_f32 v3, v6, v7
	v_cvt_pk_bf16_f32 v4, v14, v15
	v_cvt_pk_bf16_f32 v5, v12, v13
	global_store_dwordx4 v[18:19], v[2:5], off offset:256
	s_and_saveexec_b64 s[20:21], s[2:3]
	s_cbranch_execz .LBB0_950
	v_lshl_add_u64 v[2:3], v[16:17], 2, s[12:13]
	s_waitcnt lgkmcnt(0)
	v_add_f32_e32 v0, v0, v1
	global_atomic_add_f32 v[2:3], v0, off
